# tile order panel groups 5,4,4,4 for gemm1/gemmG/gemm4
# speedup vs baseline: 1.0418x; 1.0008x over previous
.LBB0_154:
	s_cmp_ge_u32 s3, 150
	s_cbranch_scc1 .Lto_g1_0
	s_sub_u32 s99, s3, 0
	s_mul_hi_u32 s98, s99, 0xcccccccd
	s_lshr_b32 s98, s98, 2
	s_mul_i32 s100, s98, 5
	s_sub_u32 s99, s99, s100
	s_branch .Lto_j_0
.Lto_g1_0:
	s_cmp_ge_u32 s3, 270
	s_cbranch_scc1 .Lto_g2_0
	s_sub_u32 s99, s3, 150
	s_lshr_b32 s98, s99, 2
	s_and_b32 s99, s99, 3
	s_add_u32 s99, s99, 5
	s_branch .Lto_j_0
.Lto_g2_0:
	s_cmp_ge_u32 s3, 390
	s_cbranch_scc1 .Lto_g3_0
	s_sub_u32 s99, s3, 270
	s_lshr_b32 s98, s99, 2
	s_and_b32 s99, s99, 3
	s_add_u32 s99, s99, 9
	s_branch .Lto_j_0
.Lto_g3_0:
	s_sub_u32 s99, s3, 390
	s_lshr_b32 s98, s99, 2
	s_and_b32 s99, s99, 3
	s_add_u32 s99, s99, 13

.LBB0_608:
	s_cmp_ge_u32 s3, 160
	s_cbranch_scc1 .Lto_g1_1
	s_sub_u32 s99, s3, 0
	s_mul_hi_u32 s98, s99, 0xcccccccd
	s_lshr_b32 s98, s98, 2
	s_mul_i32 s100, s98, 5
	s_sub_u32 s99, s99, s100
	s_branch .Lto_j_1
.Lto_g1_1:
	s_cmp_ge_u32 s3, 288
	s_cbranch_scc1 .Lto_g2_1
	s_sub_u32 s99, s3, 160
	s_lshr_b32 s98, s99, 2
	s_and_b32 s99, s99, 3
	s_add_u32 s99, s99, 5
	s_branch .Lto_j_1
.Lto_g2_1:
	s_cmp_ge_u32 s3, 416
	s_cbranch_scc1 .Lto_g3_1
	s_sub_u32 s99, s3, 288
	s_lshr_b32 s98, s99, 2
	s_and_b32 s99, s99, 3
	s_add_u32 s99, s99, 9
	s_branch .Lto_j_1
.Lto_g3_1:
	s_sub_u32 s99, s3, 416
	s_lshr_b32 s98, s99, 2
	s_and_b32 s99, s99, 3
	s_add_u32 s99, s99, 13

.LBB0_882:
	s_cmp_ge_u32 s3, 220
	s_cbranch_scc1 .Lto_g1_2
	s_sub_u32 s99, s3, 0
	s_mul_hi_u32 s98, s99, 0xcccccccd
	s_lshr_b32 s98, s98, 2
	s_mul_i32 s100, s98, 5
	s_sub_u32 s99, s99, s100
	s_branch .Lto_j_2
.Lto_g1_2:
	s_cmp_ge_u32 s3, 396
	s_cbranch_scc1 .Lto_g2_2
	s_sub_u32 s99, s3, 220
	s_lshr_b32 s98, s99, 2
	s_and_b32 s99, s99, 3
	s_add_u32 s99, s99, 5
	s_branch .Lto_j_2
.Lto_g2_2:
	s_cmp_ge_u32 s3, 572
	s_cbranch_scc1 .Lto_g3_2
	s_sub_u32 s99, s3, 396
	s_lshr_b32 s98, s99, 2
	s_and_b32 s99, s99, 3
	s_add_u32 s99, s99, 9
	s_branch .Lto_j_2
.Lto_g3_2:
	s_sub_u32 s99, s3, 572
	s_lshr_b32 s98, s99, 2
	s_and_b32 s99, s99, 3
	s_add_u32 s99, s99, 13
